# v77 + global (2-level) barrier at the three layer boundaries (seams before MIXPROJ of layers 1-3), XCD-local elsewhere
# speedup vs baseline: 1.0024x; 1.0010x over previous
; #define LAS __attribute__((address_space(3)))
; __device__ __forceinline__ unsigned xb_xcc_id() { return (unsigned)__builtin_amdgcn_s_getreg((3 << 11) | 20) & 0xFu; }
; __global__ void __launch_bounds__(NWAVES * 64, 2) trunk_fwd(Args args) {
;     ...
;         }
;         if (ph + 1 < ph_hi) { XcdBarrier xb_; xb_.bar = (unsigned*)ws; xb_.x = xb_xcc_id(); xb_.st = (volatile LAS unsigned*)(L + XB_ST_OFF); xcd_barrier(xb_); }
.LBB0_652:
	s_andn2_saveexec_b64 s[8:9], s[8:9]
	s_cbranch_execz .LBB0_169
	s_mov_b64 s[8:9], exec
	s_waitcnt lgkmcnt(0)
	v_readlane_b32 s0, v255, 9
	s_lshl_b32 s0, 1, s0
	s_and_b32 s0, s0, 0x1fbf7ef8
	s_cbranch_scc0 .Lxb_global
	v_readlane_b32 s0, v255, 42
	s_cmp_eq_u32 s0, 0
	s_cbranch_scc1 .Lxb_local
